# swiglu epilogue: r^2 folded into the sigmoid denominator with one fma per output (drops the b multiply chain), stacked on pair-combined row-stat reductions
# baseline (speedup 1.0000x reference)
.LBB0_402:
	s_add_u32 s20, s18, 0xfffc0080
	s_addc_u32 s21, s19, -1
	s_add_i32 s41, 0, 0x10000
	ds_read_b128 v[138:141], v218
	ds_read_b128 v[148:151], v218 offset:1024
	ds_read_b128 v[152:155], v218 offset:2048
	ds_read_b128 v[156:159], v218 offset:3072
	s_cmp_eq_u32 s40, 12
	s_cselect_b32 s23, s1, s21
	s_cselect_b32 s22, s9, s20
	s_cselect_b32 s21, s11, s39
	s_cselect_b32 s20, s33, s38
	s_add_i32 m0, s17, 0xc000
	ds_read_b128 v[160:163], v146
	ds_read_b128 v[164:167], v146 offset:1024
	ds_read_b128 v[168:171], v146 offset:2048
	ds_read_b128 v[172:175], v146 offset:3072
	ds_read_b128 v[176:179], v146 offset:4096
	ds_read_b128 v[180:183], v146 offset:5120
	ds_read_b128 v[184:187], v146 offset:6144
	ds_read_b128 v[188:191], v146 offset:7168
	global_load_lds_dwordx4 v136, s[18:19]
	s_add_i32 m0, s17, 0xe000
	s_nop 0
	global_load_lds_dwordx4 v134, s[18:19]
	s_waitcnt lgkmcnt(8)
	s_barrier
	s_waitcnt lgkmcnt(0)
	v_mfma_f32_16x16x32_bf16 v[124:127], v[138:141], v[160:163], v[124:127]
	v_mfma_f32_16x16x32_bf16 v[116:119], v[152:155], v[160:163], v[116:119]
	v_mfma_f32_16x16x32_bf16 v[108:111], v[138:141], v[168:171], v[108:111]
	v_mfma_f32_16x16x32_bf16 v[100:103], v[152:155], v[168:171], v[100:103]
	v_mfma_f32_16x16x32_bf16 v[92:95], v[138:141], v[176:179], v[92:95]
	v_mfma_f32_16x16x32_bf16 v[84:87], v[152:155], v[176:179], v[84:87]
	v_mfma_f32_16x16x32_bf16 v[76:79], v[138:141], v[184:187], v[76:79]
	v_mfma_f32_16x16x32_bf16 v[68:71], v[152:155], v[184:187], v[68:71]
	v_mfma_f32_16x16x32_bf16 v[124:127], v[148:151], v[164:167], v[124:127]
	v_mfma_f32_16x16x32_bf16 v[116:119], v[156:159], v[164:167], v[116:119]
	v_mfma_f32_16x16x32_bf16 v[108:111], v[148:151], v[172:175], v[108:111]
	v_mfma_f32_16x16x32_bf16 v[100:103], v[156:159], v[172:175], v[100:103]
	v_mfma_f32_16x16x32_bf16 v[92:95], v[148:151], v[180:183], v[92:95]
	v_mfma_f32_16x16x32_bf16 v[84:87], v[156:159], v[180:183], v[84:87]
	v_mfma_f32_16x16x32_bf16 v[76:79], v[148:151], v[188:191], v[76:79]
	v_mfma_f32_16x16x32_bf16 v[68:71], v[156:159], v[188:191], v[68:71]
	s_barrier
	s_add_i32 s44, 0, 0x14000
	s_add_i32 s41, s41, s28
	ds_read_b128 v[198:201], v219
	ds_read_b128 v[206:209], v219 offset:1024
	ds_read_b128 v[210:213], v219 offset:2048
	ds_read_b128 v[214:217], v219 offset:3072
	s_mov_b32 m0, s41
	s_nop 0
	global_load_lds_dwordx4 v192, s[20:21]
	s_add_i32 m0, s41, 0x2000
	s_nop 0
	global_load_lds_dwordx4 v128, s[20:21]
	s_barrier
	s_waitcnt lgkmcnt(0)
	v_mfma_f32_16x16x32_bf16 v[120:123], v[198:201], v[160:163], v[120:123]
	v_mfma_f32_16x16x32_bf16 v[112:115], v[210:213], v[160:163], v[112:115]
	v_mfma_f32_16x16x32_bf16 v[104:107], v[198:201], v[168:171], v[104:107]
	v_mfma_f32_16x16x32_bf16 v[96:99], v[210:213], v[168:171], v[96:99]
	v_mfma_f32_16x16x32_bf16 v[88:91], v[198:201], v[176:179], v[88:91]
	v_mfma_f32_16x16x32_bf16 v[80:83], v[210:213], v[176:179], v[80:83]
	v_mfma_f32_16x16x32_bf16 v[72:75], v[198:201], v[184:187], v[72:75]
	v_mfma_f32_16x16x32_bf16 v[64:67], v[210:213], v[184:187], v[64:67]
	v_mfma_f32_16x16x32_bf16 v[120:123], v[206:209], v[164:167], v[120:123]
	v_mfma_f32_16x16x32_bf16 v[112:115], v[214:217], v[164:167], v[112:115]
	v_mfma_f32_16x16x32_bf16 v[104:107], v[206:209], v[172:175], v[104:107]
	v_mfma_f32_16x16x32_bf16 v[96:99], v[214:217], v[172:175], v[96:99]
	v_mfma_f32_16x16x32_bf16 v[88:91], v[206:209], v[180:183], v[88:91]
	v_mfma_f32_16x16x32_bf16 v[80:83], v[214:217], v[180:183], v[80:83]
	v_mfma_f32_16x16x32_bf16 v[72:75], v[206:209], v[188:191], v[72:75]
	v_mfma_f32_16x16x32_bf16 v[64:67], v[214:217], v[188:191], v[64:67]
	s_mov_b32 m0, s17
	s_add_u32 vcc_lo, s22, 0x80
	s_addc_u32 vcc_hi, s23, 0
	s_barrier
	ds_read_b128 v[160:163], v146 offset:16384
	ds_read_b128 v[164:167], v146 offset:17408
	ds_read_b128 v[168:171], v146 offset:18432
	ds_read_b128 v[172:175], v146 offset:19456
	ds_read_b128 v[176:179], v146 offset:20480
	ds_read_b128 v[180:183], v146 offset:21504
	ds_read_b128 v[184:187], v146 offset:22528
	ds_read_b128 v[188:191], v146 offset:23552
	global_load_lds_dwordx4 v132, s[22:23]
	s_mov_b32 m0, s29
	s_nop 0
	global_load_lds_dwordx4 v130, s[22:23]
	s_barrier
	s_waitcnt lgkmcnt(0)
	v_mfma_f32_16x16x32_bf16 v[60:63], v[138:141], v[160:163], v[60:63]
	v_mfma_f32_16x16x32_bf16 v[52:55], v[152:155], v[160:163], v[52:55]
	v_mfma_f32_16x16x32_bf16 v[44:47], v[138:141], v[168:171], v[44:47]
	v_mfma_f32_16x16x32_bf16 v[36:39], v[152:155], v[168:171], v[36:39]
	v_mfma_f32_16x16x32_bf16 v[28:31], v[138:141], v[176:179], v[28:31]
	v_mfma_f32_16x16x32_bf16 v[20:23], v[152:155], v[176:179], v[20:23]
	v_mfma_f32_16x16x32_bf16 v[12:15], v[138:141], v[184:187], v[12:15]
	v_mfma_f32_16x16x32_bf16 v[4:7], v[152:155], v[184:187], v[4:7]
	v_mfma_f32_16x16x32_bf16 v[60:63], v[148:151], v[164:167], v[60:63]
	v_mfma_f32_16x16x32_bf16 v[52:55], v[156:159], v[164:167], v[52:55]
	v_mfma_f32_16x16x32_bf16 v[44:47], v[148:151], v[172:175], v[44:47]
	v_mfma_f32_16x16x32_bf16 v[36:39], v[156:159], v[172:175], v[36:39]
	v_mfma_f32_16x16x32_bf16 v[28:31], v[148:151], v[180:183], v[28:31]
	v_mfma_f32_16x16x32_bf16 v[20:23], v[156:159], v[180:183], v[20:23]
	v_mfma_f32_16x16x32_bf16 v[12:15], v[148:151], v[188:191], v[12:15]
	v_mfma_f32_16x16x32_bf16 v[4:7], v[156:159], v[188:191], v[4:7]
	s_barrier
	s_add_u32 s42, s20, 0x40000
	s_addc_u32 s43, s21, 0
	s_add_i32 s41, s44, s28
	s_mov_b32 m0, s41
	s_nop 0
	global_load_lds_dwordx4 v192, s[42:43]
	s_add_i32 m0, s41, 0x2000
	s_nop 0
	global_load_lds_dwordx4 v128, s[42:43]
	s_waitcnt vmcnt(6)
	s_barrier
	v_mfma_f32_16x16x32_bf16 v[56:59], v[198:201], v[160:163], v[56:59]
	v_mfma_f32_16x16x32_bf16 v[48:51], v[210:213], v[160:163], v[48:51]
	v_mfma_f32_16x16x32_bf16 v[40:43], v[198:201], v[168:171], v[40:43]
	v_mfma_f32_16x16x32_bf16 v[32:35], v[210:213], v[168:171], v[32:35]
	v_mfma_f32_16x16x32_bf16 v[24:27], v[198:201], v[176:179], v[24:27]
	v_mfma_f32_16x16x32_bf16 v[16:19], v[210:213], v[176:179], v[16:19]
	v_mfma_f32_16x16x32_bf16 v[8:11], v[198:201], v[184:187], v[8:11]
	v_mfma_f32_16x16x32_bf16 v[0:3], v[210:213], v[184:187], v[0:3]
	v_mfma_f32_16x16x32_bf16 v[56:59], v[206:209], v[164:167], v[56:59]
	v_mfma_f32_16x16x32_bf16 v[48:51], v[214:217], v[164:167], v[48:51]
	v_mfma_f32_16x16x32_bf16 v[40:43], v[206:209], v[172:175], v[40:43]
	v_mfma_f32_16x16x32_bf16 v[32:35], v[214:217], v[172:175], v[32:35]
	v_mfma_f32_16x16x32_bf16 v[24:27], v[206:209], v[180:183], v[24:27]
	v_mfma_f32_16x16x32_bf16 v[16:19], v[214:217], v[180:183], v[16:19]
	v_mfma_f32_16x16x32_bf16 v[8:11], v[206:209], v[188:191], v[8:11]
	v_mfma_f32_16x16x32_bf16 v[0:3], v[214:217], v[188:191], v[0:3]
	s_add_i32 s41, 0, 0x18000
	s_barrier
	ds_read_b128 v[138:141], v220
	ds_read_b128 v[148:151], v220 offset:1024
	ds_read_b128 v[152:155], v220 offset:2048
	ds_read_b128 v[156:159], v220 offset:3072
	s_add_u32 s22, s22, 0x40000
	s_addc_u32 s23, s23, 0
	s_mov_b32 m0, s30
	ds_read_b128 v[160:163], v146 offset:32768
	ds_read_b128 v[164:167], v146 offset:33792
	ds_read_b128 v[168:171], v146 offset:34816
	ds_read_b128 v[172:175], v146 offset:35840
	ds_read_b128 v[176:179], v146 offset:36864
	ds_read_b128 v[180:183], v146 offset:37888
	ds_read_b128 v[184:187], v146 offset:38912
	ds_read_b128 v[188:191], v146 offset:39936
	global_load_lds_dwordx4 v132, s[22:23]
	s_mov_b32 m0, s31
	s_nop 0
	global_load_lds_dwordx4 v130, s[22:23]
	s_waitcnt lgkmcnt(8)
	s_barrier
	s_waitcnt lgkmcnt(0)
	v_mfma_f32_16x16x32_bf16 v[124:127], v[138:141], v[160:163], v[124:127]
	v_mfma_f32_16x16x32_bf16 v[116:119], v[152:155], v[160:163], v[116:119]
	v_mfma_f32_16x16x32_bf16 v[108:111], v[138:141], v[168:171], v[108:111]
	v_mfma_f32_16x16x32_bf16 v[100:103], v[152:155], v[168:171], v[100:103]
	v_mfma_f32_16x16x32_bf16 v[92:95], v[138:141], v[176:179], v[92:95]
	v_mfma_f32_16x16x32_bf16 v[84:87], v[152:155], v[176:179], v[84:87]
	v_mfma_f32_16x16x32_bf16 v[76:79], v[138:141], v[184:187], v[76:79]
	v_mfma_f32_16x16x32_bf16 v[68:71], v[152:155], v[184:187], v[68:71]
	v_mfma_f32_16x16x32_bf16 v[124:127], v[148:151], v[164:167], v[124:127]
	v_mfma_f32_16x16x32_bf16 v[116:119], v[156:159], v[164:167], v[116:119]
	v_mfma_f32_16x16x32_bf16 v[108:111], v[148:151], v[172:175], v[108:111]
	v_mfma_f32_16x16x32_bf16 v[100:103], v[156:159], v[172:175], v[100:103]
	v_mfma_f32_16x16x32_bf16 v[92:95], v[148:151], v[180:183], v[92:95]
	v_mfma_f32_16x16x32_bf16 v[84:87], v[156:159], v[180:183], v[84:87]
	v_mfma_f32_16x16x32_bf16 v[76:79], v[148:151], v[188:191], v[76:79]
	v_mfma_f32_16x16x32_bf16 v[68:71], v[156:159], v[188:191], v[68:71]
	s_barrier
	s_add_i32 s22, 0, 0x1c000
	s_add_i32 s23, s41, s28
	s_add_u32 s100, s20, 0x80
	s_addc_u32 s101, s21, 0
	s_mov_b32 m0, s23
	ds_read_b128 v[198:201], v221
	ds_read_b128 v[206:209], v221 offset:1024
	ds_read_b128 v[210:213], v221 offset:2048
	ds_read_b128 v[214:217], v221 offset:3072
	global_load_lds_dwordx4 v192, s[100:101]
	s_add_i32 m0, s23, 0x2000
	s_nop 0
	global_load_lds_dwordx4 v128, s[100:101]
	s_barrier
	s_waitcnt lgkmcnt(0)
	v_mfma_f32_16x16x32_bf16 v[120:123], v[198:201], v[160:163], v[120:123]
	v_mfma_f32_16x16x32_bf16 v[112:115], v[210:213], v[160:163], v[112:115]
	v_mfma_f32_16x16x32_bf16 v[104:107], v[198:201], v[168:171], v[104:107]
	v_mfma_f32_16x16x32_bf16 v[96:99], v[210:213], v[168:171], v[96:99]
	v_mfma_f32_16x16x32_bf16 v[88:91], v[198:201], v[176:179], v[88:91]
	v_mfma_f32_16x16x32_bf16 v[80:83], v[210:213], v[176:179], v[80:83]
	v_mfma_f32_16x16x32_bf16 v[72:75], v[198:201], v[184:187], v[72:75]
	v_mfma_f32_16x16x32_bf16 v[64:67], v[210:213], v[184:187], v[64:67]
	v_mfma_f32_16x16x32_bf16 v[120:123], v[206:209], v[164:167], v[120:123]
	v_mfma_f32_16x16x32_bf16 v[112:115], v[214:217], v[164:167], v[112:115]
	v_mfma_f32_16x16x32_bf16 v[104:107], v[206:209], v[172:175], v[104:107]
	v_mfma_f32_16x16x32_bf16 v[96:99], v[214:217], v[172:175], v[96:99]
	v_mfma_f32_16x16x32_bf16 v[88:91], v[206:209], v[180:183], v[88:91]
	v_mfma_f32_16x16x32_bf16 v[80:83], v[214:217], v[180:183], v[80:83]
	v_mfma_f32_16x16x32_bf16 v[72:75], v[206:209], v[188:191], v[72:75]
	v_mfma_f32_16x16x32_bf16 v[64:67], v[214:217], v[188:191], v[64:67]
	s_mov_b32 m0, s34
	s_barrier
	ds_read_b128 v[160:163], v146 offset:49152
	ds_read_b128 v[164:167], v146 offset:50176
	ds_read_b128 v[168:171], v146 offset:51200
	ds_read_b128 v[172:175], v146 offset:52224
	ds_read_b128 v[176:179], v146 offset:53248
	ds_read_b128 v[180:183], v146 offset:54272
	ds_read_b128 v[184:187], v146 offset:55296
	ds_read_b128 v[188:191], v146 offset:56320
	global_load_lds_dwordx4 v132, vcc
	s_mov_b32 m0, s35
	s_nop 0
	global_load_lds_dwordx4 v130, vcc
	s_barrier
	s_waitcnt lgkmcnt(0)
	v_mfma_f32_16x16x32_bf16 v[60:63], v[138:141], v[160:163], v[60:63]
	v_mfma_f32_16x16x32_bf16 v[52:55], v[152:155], v[160:163], v[52:55]
	v_mfma_f32_16x16x32_bf16 v[44:47], v[138:141], v[168:171], v[44:47]
	v_mfma_f32_16x16x32_bf16 v[36:39], v[152:155], v[168:171], v[36:39]
	v_mfma_f32_16x16x32_bf16 v[28:31], v[138:141], v[176:179], v[28:31]
	v_mfma_f32_16x16x32_bf16 v[20:23], v[152:155], v[176:179], v[20:23]
	v_mfma_f32_16x16x32_bf16 v[12:15], v[138:141], v[184:187], v[12:15]
	v_mfma_f32_16x16x32_bf16 v[4:7], v[152:155], v[184:187], v[4:7]
	v_mfma_f32_16x16x32_bf16 v[60:63], v[148:151], v[164:167], v[60:63]
	v_mfma_f32_16x16x32_bf16 v[52:55], v[156:159], v[164:167], v[52:55]
	v_mfma_f32_16x16x32_bf16 v[44:47], v[148:151], v[172:175], v[44:47]
	v_mfma_f32_16x16x32_bf16 v[36:39], v[156:159], v[172:175], v[36:39]
	v_mfma_f32_16x16x32_bf16 v[28:31], v[148:151], v[180:183], v[28:31]
	v_mfma_f32_16x16x32_bf16 v[20:23], v[156:159], v[180:183], v[20:23]
	v_mfma_f32_16x16x32_bf16 v[12:15], v[148:151], v[188:191], v[12:15]
	v_mfma_f32_16x16x32_bf16 v[4:7], v[156:159], v[188:191], v[4:7]
	s_barrier
	s_add_u32 s20, s20, 0x40080
	s_addc_u32 s21, s21, 0
	s_add_i32 s22, s22, s28
	s_mov_b32 m0, s22
	s_nop 0
	global_load_lds_dwordx4 v192, s[20:21]
	s_add_i32 m0, s22, 0x2000
	s_nop 0
	global_load_lds_dwordx4 v128, s[20:21]
	s_waitcnt vmcnt(6)
	s_barrier
	v_mfma_f32_16x16x32_bf16 v[56:59], v[198:201], v[160:163], v[56:59]
	v_mfma_f32_16x16x32_bf16 v[48:51], v[210:213], v[160:163], v[48:51]
	v_mfma_f32_16x16x32_bf16 v[40:43], v[198:201], v[168:171], v[40:43]
	v_mfma_f32_16x16x32_bf16 v[32:35], v[210:213], v[168:171], v[32:35]
	v_mfma_f32_16x16x32_bf16 v[24:27], v[198:201], v[176:179], v[24:27]
	v_mfma_f32_16x16x32_bf16 v[16:19], v[210:213], v[176:179], v[16:19]
	v_mfma_f32_16x16x32_bf16 v[8:11], v[198:201], v[184:187], v[8:11]
	v_mfma_f32_16x16x32_bf16 v[0:3], v[210:213], v[184:187], v[0:3]
	v_mfma_f32_16x16x32_bf16 v[56:59], v[206:209], v[164:167], v[56:59]
	v_mfma_f32_16x16x32_bf16 v[48:51], v[214:217], v[164:167], v[48:51]
	v_mfma_f32_16x16x32_bf16 v[40:43], v[206:209], v[172:175], v[40:43]
	v_mfma_f32_16x16x32_bf16 v[32:35], v[214:217], v[172:175], v[32:35]
	v_mfma_f32_16x16x32_bf16 v[24:27], v[206:209], v[180:183], v[24:27]
	v_mfma_f32_16x16x32_bf16 v[16:19], v[214:217], v[180:183], v[16:19]
	v_mfma_f32_16x16x32_bf16 v[8:11], v[206:209], v[188:191], v[8:11]
	v_mfma_f32_16x16x32_bf16 v[0:3], v[214:217], v[188:191], v[0:3]
	s_add_i32 s40, s40, 2
	s_add_u32 s38, s38, 0x100
	s_addc_u32 s39, s39, 0
	s_add_u32 s18, s18, 0x100
	s_addc_u32 s19, s19, 0
	s_cmp_gt_u32 s40, 13
	s_barrier
	s_cbranch_scc0 .LBB0_402
	v_mov_b32_e32 v139, v252
	s_lshl_b32 s9, s16, 8
	v_readfirstlane_b32 s1, v139
	s_ashr_i32 s11, s1, 2
	s_andn2_b32 s11, s11, 63
	s_lshr_b32 s1, s1, 1
	s_add_i32 s11, s11, s9
	s_lshl_b32 s0, s0, 7
	s_and_b32 s1, s1, 0x60
	v_and_or_b32 v138, v139, 15, s11
	s_or_b32 s0, s1, s0
	v_lshrrev_b32_e32 v139, 1, v139
	v_and_or_b32 v142, v139, 24, s0
	v_ashrrev_i32_e32 v139, 31, v138
	v_lshl_add_u64 v[140:141], v[138:139], 2, s[6:7]
	v_pk_mul_f32 v[120:121], v[124:125], v[120:121]
	v_pk_mul_f32 v[122:123], v[126:127], v[122:123]
	v_pk_mul_f32 v[112:113], v[116:117], v[112:113]
	v_pk_mul_f32 v[114:115], v[118:119], v[114:115]
	v_ashrrev_i32_e32 v143, 31, v142
	s_movk_i32 s9, 0x1600
	v_pk_mul_f32 v[104:105], v[108:109], v[104:105]
	v_pk_mul_f32 v[106:107], v[110:111], v[106:107]
	v_pk_mul_f32 v[96:97], v[100:101], v[96:97]
	v_or_b32_e32 v150, 16, v138
	v_pk_mul_f32 v[98:99], v[102:103], v[98:99]
	v_pk_mul_f32 v[88:89], v[92:93], v[88:89]
	v_pk_mul_f32 v[90:91], v[94:95], v[90:91]
	v_pk_mul_f32 v[80:81], v[84:85], v[80:81]
	v_or_b32_e32 v148, 32, v138
	v_pk_mul_f32 v[82:83], v[86:87], v[82:83]
	v_pk_mul_f32 v[72:73], v[76:77], v[72:73]
	v_pk_mul_f32 v[74:75], v[78:79], v[74:75]
	v_pk_mul_f32 v[64:65], v[68:69], v[64:65]
	v_or_b32_e32 v139, 48, v138
	v_pk_mul_f32 v[66:67], v[70:71], v[66:67]
	v_pk_mul_f32 v[56:57], v[60:61], v[56:57]
	v_pk_mul_f32 v[58:59], v[62:63], v[58:59]
	v_pk_mul_f32 v[48:49], v[52:53], v[48:49]
	v_pk_mul_f32 v[50:51], v[54:55], v[50:51]
	v_pk_mul_f32 v[40:41], v[44:45], v[40:41]
	v_pk_mul_f32 v[42:43], v[46:47], v[42:43]
	v_pk_mul_f32 v[32:33], v[36:37], v[32:33]
	v_pk_mul_f32 v[34:35], v[38:39], v[34:35]
	v_pk_mul_f32 v[24:25], v[28:29], v[24:25]
	v_pk_mul_f32 v[26:27], v[30:31], v[26:27]
	v_pk_mul_f32 v[16:17], v[20:21], v[16:17]
	v_pk_mul_f32 v[18:19], v[22:23], v[18:19]
	v_pk_mul_f32 v[8:9], v[12:13], v[8:9]
	v_pk_mul_f32 v[10:11], v[14:15], v[10:11]
	v_pk_mul_f32 v[0:1], v[4:5], v[0:1]
	v_pk_mul_f32 v[2:3], v[6:7], v[2:3]
	s_mov_b32 s16, s8
	s_mov_b64 s[18:19], s[14:15]
	s_mov_b64 s[20:21], s[12:13]
	v_fmamk_f32 v239, v231, 0x3a800000, v194
	s_nop 0
	v_rsq_f32_e32 v144, v239
	s_nop 0
	v_mul_f32_e32 v152, 0xbfb8aa3b, v144
	v_pk_mul_f32 v[156:157], v[124:125], v[152:153] op_sel_hi:[1,0]
	v_pk_mul_f32 v[154:155], v[126:127], v[152:153] op_sel_hi:[1,0]
	v_exp_f32_e32 v153, v156
	s_nop 0
	v_fma_f32 v153, v153, v239, v239
	v_rcp_f32_e32 v156, v153
	v_exp_f32_e32 v153, v157
	s_nop 0
	v_fma_f32 v153, v153, v239, v239
	v_rcp_f32_e32 v157, v153
	v_exp_f32_e32 v153, v154
	s_nop 0
	v_fma_f32 v153, v153, v239, v239
	v_rcp_f32_e32 v154, v153
	v_exp_f32_e32 v153, v155
	v_pk_mul_f32 v[120:121], v[120:121], v[156:157]
	v_fma_f32 v153, v153, v239, v239
	v_rcp_f32_e32 v155, v153
	v_cvt_pk_bf16_f32 v124, v121, s0
	v_cvt_pk_bf16_f32 v120, v120, s0
	v_readlane_b32 s0, v254, 29
	s_nop 0
	v_pk_mul_f32 v[122:123], v[122:123], v[154:155]
	v_readlane_b32 s1, v254, 30
	v_cvt_pk_bf16_f32 v121, v122, v123
	v_lshlrev_b32_e32 v122, 16, v124
	v_pk_mul_f32 v[124:125], v[116:117], v[152:153] op_sel_hi:[1,0]
	v_or_b32_sdwa v120, v122, v120 dst_sel:DWORD dst_unused:UNUSED_PAD src0_sel:DWORD src1_sel:WORD_0
	v_pk_mul_f32 v[122:123], v[118:119], v[152:153] op_sel_hi:[1,0]
	v_exp_f32_e32 v124, v124
	v_exp_f32_e32 v125, v125
	v_exp_f32_e32 v122, v122
	v_exp_f32_e32 v123, v123
	v_fma_f32 v124, v124, v239, v239
	v_fma_f32 v125, v125, v239, v239
	v_rcp_f32_e32 v124, v124
	v_rcp_f32_e32 v125, v125
	v_fma_f32 v122, v122, v239, v239
	v_fma_f32 v123, v123, v239, v239
	v_rcp_f32_e32 v122, v122
	v_rcp_f32_e32 v123, v123
	s_nop 0
	v_pk_mul_f32 v[112:113], v[112:113], v[124:125]
	s_nop 0
	v_pk_mul_f32 v[114:115], v[114:115], v[122:123]
	v_cvt_pk_bf16_f32 v122, v112, v113
	v_mov_b64_e32 v[112:113], s[0:1]
	v_cvt_pk_bf16_f32 v123, v114, v115
	v_mad_i64_i32 v[116:117], s[0:1], v138, s9, v[112:113]
	v_lshlrev_b64 v[114:115], 1, v[142:143]
	v_lshl_add_u64 v[116:117], v[116:117], 0, v[114:115]
	global_store_dwordx4 v[116:117], v[120:123], off
	v_fmamk_f32 v239, v232, 0x3a800000, v194
	s_nop 0
	v_rsq_f32_e32 v116, v239
	s_nop 0
	v_mul_f32_e32 v118, 0xbfb8aa3b, v116
	v_pk_mul_f32 v[120:121], v[108:109], v[118:119] op_sel_hi:[1,0]
	v_pk_mul_f32 v[122:123], v[110:111], v[118:119] op_sel_hi:[1,0]
	v_exp_f32_e32 v117, v120
	s_nop 0
	v_fma_f32 v117, v117, v239, v239
	v_rcp_f32_e32 v120, v117
	v_exp_f32_e32 v117, v121
	s_nop 0
	v_fma_f32 v117, v117, v239, v239
	v_rcp_f32_e32 v121, v117
	v_exp_f32_e32 v117, v122
	s_nop 0
	v_fma_f32 v117, v117, v239, v239
	v_rcp_f32_e32 v122, v117
	v_exp_f32_e32 v117, v123
	s_nop 0
	v_fma_f32 v117, v117, v239, v239
	v_rcp_f32_e32 v123, v117
	s_nop 0
	v_pk_mul_f32 v[104:105], v[104:105], v[120:121]
	s_nop 0
	v_pk_mul_f32 v[106:107], v[106:107], v[122:123]
	v_cvt_pk_bf16_f32 v108, v105, s0
	v_cvt_pk_bf16_f32 v104, v104, s0
	v_cvt_pk_bf16_f32 v105, v106, v107
	v_lshlrev_b32_e32 v106, 16, v108
	v_pk_mul_f32 v[108:109], v[100:101], v[118:119] op_sel_hi:[1,0]
	v_or_b32_sdwa v104, v106, v104 dst_sel:DWORD dst_unused:UNUSED_PAD src0_sel:DWORD src1_sel:WORD_0
	v_pk_mul_f32 v[106:107], v[102:103], v[118:119] op_sel_hi:[1,0]
	v_exp_f32_e32 v108, v108
	v_exp_f32_e32 v109, v109
	v_exp_f32_e32 v106, v106
	v_exp_f32_e32 v107, v107
	v_fma_f32 v108, v108, v239, v239
	v_fma_f32 v109, v109, v239, v239
	v_rcp_f32_e32 v108, v108
	v_rcp_f32_e32 v109, v109
	v_fma_f32 v106, v106, v239, v239
	v_fma_f32 v107, v107, v239, v239
	v_rcp_f32_e32 v106, v106
	v_rcp_f32_e32 v107, v107
	s_nop 0
	v_pk_mul_f32 v[96:97], v[96:97], v[108:109]
	s_nop 0
	v_pk_mul_f32 v[98:99], v[98:99], v[106:107]
	v_cvt_pk_bf16_f32 v106, v96, v97
	v_mad_i64_i32 v[96:97], s[0:1], v150, s9, v[112:113]
	v_cvt_pk_bf16_f32 v107, v98, v99
	v_lshl_add_u64 v[96:97], v[96:97], 0, v[114:115]
	global_store_dwordx4 v[96:97], v[104:107], off
	v_fmamk_f32 v239, v233, 0x3a800000, v194
	s_nop 0
	v_rsq_f32_e32 v96, v239
	s_nop 0
	v_mov_b32_e32 v97, v96
	v_mul_f32_e32 v96, 0xbfb8aa3b, v97
	v_pk_mul_f32 v[102:103], v[92:93], v[96:97] op_sel_hi:[1,0]
	s_nop 0
	v_pk_mul_f32 v[100:101], v[94:95], v[96:97] op_sel_hi:[1,0]
	v_exp_f32_e32 v97, v102
	s_nop 0
	v_fma_f32 v97, v97, v239, v239
	v_rcp_f32_e32 v102, v97
	v_exp_f32_e32 v97, v103
	s_nop 0
	v_fma_f32 v97, v97, v239, v239
	v_rcp_f32_e32 v103, v97
	v_exp_f32_e32 v97, v100
	s_nop 0
	v_fma_f32 v97, v97, v239, v239
	v_rcp_f32_e32 v100, v97
	v_exp_f32_e32 v97, v101
	v_pk_mul_f32 v[88:89], v[88:89], v[102:103]
	v_fma_f32 v97, v97, v239, v239
	v_rcp_f32_e32 v101, v97
	v_cvt_pk_bf16_f32 v92, v89, s0
	v_cvt_pk_bf16_f32 v88, v88, s0
	s_nop 0
	v_pk_mul_f32 v[90:91], v[90:91], v[100:101]
	s_nop 0
	v_cvt_pk_bf16_f32 v89, v90, v91
	v_lshlrev_b32_e32 v90, 16, v92
	v_pk_mul_f32 v[92:93], v[84:85], v[96:97] op_sel_hi:[1,0]
	v_or_b32_sdwa v88, v90, v88 dst_sel:DWORD dst_unused:UNUSED_PAD src0_sel:DWORD src1_sel:WORD_0
	v_pk_mul_f32 v[90:91], v[86:87], v[96:97] op_sel_hi:[1,0]
	v_exp_f32_e32 v92, v92
	v_exp_f32_e32 v93, v93
	v_exp_f32_e32 v90, v90
	v_exp_f32_e32 v91, v91
	v_fma_f32 v92, v92, v239, v239
	v_fma_f32 v93, v93, v239, v239
	v_rcp_f32_e32 v92, v92
	v_rcp_f32_e32 v93, v93
	v_fma_f32 v90, v90, v239, v239
	v_fma_f32 v91, v91, v239, v239
	v_rcp_f32_e32 v90, v90
	v_rcp_f32_e32 v91, v91
	s_nop 0
	v_pk_mul_f32 v[80:81], v[80:81], v[92:93]
	s_nop 0
	v_pk_mul_f32 v[82:83], v[82:83], v[90:91]
	v_cvt_pk_bf16_f32 v90, v80, v81
	v_mad_i64_i32 v[80:81], s[0:1], v148, s9, v[112:113]
	v_cvt_pk_bf16_f32 v91, v82, v83
	v_lshl_add_u64 v[80:81], v[80:81], 0, v[114:115]
	global_store_dwordx4 v[80:81], v[88:91], off
	v_fmamk_f32 v239, v234, 0x3a800000, v194
	s_nop 0
	v_rsq_f32_e32 v80, v239
	s_nop 0
	v_mov_b32_e32 v81, v80
	v_mul_f32_e32 v80, 0xbfb8aa3b, v81
	v_pk_mul_f32 v[86:87], v[76:77], v[80:81] op_sel_hi:[1,0]
	s_nop 0
	v_pk_mul_f32 v[84:85], v[78:79], v[80:81] op_sel_hi:[1,0]
	v_exp_f32_e32 v81, v86
	s_nop 0
	v_fma_f32 v81, v81, v239, v239
	v_rcp_f32_e32 v86, v81
	v_exp_f32_e32 v81, v87
	s_nop 0
	v_fma_f32 v81, v81, v239, v239
	v_rcp_f32_e32 v87, v81
	v_exp_f32_e32 v81, v84
	s_nop 0
	v_fma_f32 v81, v81, v239, v239
	v_rcp_f32_e32 v84, v81
	v_exp_f32_e32 v81, v85
	v_pk_mul_f32 v[72:73], v[72:73], v[86:87]
	v_fma_f32 v81, v81, v239, v239
	v_rcp_f32_e32 v85, v81
	v_cvt_pk_bf16_f32 v76, v73, s0
	v_cvt_pk_bf16_f32 v72, v72, s0
	s_nop 0
	v_pk_mul_f32 v[74:75], v[74:75], v[84:85]
	s_nop 0
	v_cvt_pk_bf16_f32 v73, v74, v75
	v_lshlrev_b32_e32 v74, 16, v76
	v_pk_mul_f32 v[76:77], v[68:69], v[80:81] op_sel_hi:[1,0]
	v_or_b32_sdwa v72, v74, v72 dst_sel:DWORD dst_unused:UNUSED_PAD src0_sel:DWORD src1_sel:WORD_0
	v_pk_mul_f32 v[74:75], v[70:71], v[80:81] op_sel_hi:[1,0]
	v_exp_f32_e32 v76, v76
	v_exp_f32_e32 v77, v77
	v_exp_f32_e32 v74, v74
	v_exp_f32_e32 v75, v75
	v_fma_f32 v76, v76, v239, v239
	v_fma_f32 v77, v77, v239, v239
	v_rcp_f32_e32 v76, v76
	v_rcp_f32_e32 v77, v77
	v_fma_f32 v74, v74, v239, v239
	v_fma_f32 v75, v75, v239, v239
	v_rcp_f32_e32 v74, v74
	v_rcp_f32_e32 v75, v75
	s_nop 0
	v_pk_mul_f32 v[64:65], v[64:65], v[76:77]
	v_add_u32_e32 v69, 0x90, v138
	s_nop 0
	v_pk_mul_f32 v[66:67], v[66:67], v[74:75]
	v_cvt_pk_bf16_f32 v74, v64, v65
	v_mad_i64_i32 v[64:65], s[0:1], v139, s9, v[112:113]
	v_cvt_pk_bf16_f32 v75, v66, v67
	v_lshl_add_u64 v[64:65], v[64:65], 0, v[114:115]
	global_store_dwordx4 v[64:65], v[72:75], off
	v_add_u32_e32 v67, 0x80, v138
	v_add_u32_e32 v66, 0xa0, v138
	v_add_u32_e32 v64, 0xb0, v138
	v_fmamk_f32 v239, v235, 0x3a800000, v194
	s_nop 0
	v_rsq_f32_e32 v68, v239
	s_nop 0
	v_mov_b32_e32 v70, v68
	v_mul_f32_e32 v68, 0xbfb8aa3b, v70
	v_pk_mul_f32 v[74:75], v[60:61], v[68:69] op_sel_hi:[1,0]
	v_pk_mul_f32 v[72:73], v[62:63], v[68:69] op_sel_hi:[1,0]
	v_exp_f32_e32 v74, v74
	v_exp_f32_e32 v75, v75
	v_exp_f32_e32 v72, v72
	v_exp_f32_e32 v73, v73
	v_fma_f32 v74, v74, v239, v239
	v_fma_f32 v75, v75, v239, v239
	v_rcp_f32_e32 v74, v74
	v_rcp_f32_e32 v75, v75
	v_fma_f32 v72, v72, v239, v239
	v_fma_f32 v73, v73, v239, v239
	v_rcp_f32_e32 v72, v72
	v_rcp_f32_e32 v73, v73
	s_nop 0
	s_nop 0
	v_pk_mul_f32 v[56:57], v[56:57], v[74:75]
	s_nop 0
	v_pk_mul_f32 v[58:59], v[58:59], v[72:73]
	v_cvt_pk_bf16_f32 v60, v57, s0
	v_cvt_pk_bf16_f32 v56, v56, s0
	v_cvt_pk_bf16_f32 v57, v58, v59
	v_lshlrev_b32_e32 v58, 16, v60
	v_pk_mul_f32 v[60:61], v[52:53], v[68:69] op_sel_hi:[1,0]
	v_or_b32_sdwa v56, v58, v56 dst_sel:DWORD dst_unused:UNUSED_PAD src0_sel:DWORD src1_sel:WORD_0
	v_pk_mul_f32 v[58:59], v[54:55], v[68:69] op_sel_hi:[1,0]
	v_exp_f32_e32 v60, v60
	v_exp_f32_e32 v61, v61
	v_exp_f32_e32 v58, v58
	v_exp_f32_e32 v59, v59
	v_fma_f32 v60, v60, v239, v239
	v_fma_f32 v61, v61, v239, v239
	v_rcp_f32_e32 v60, v60
	v_rcp_f32_e32 v61, v61
	v_fma_f32 v58, v58, v239, v239
	v_fma_f32 v59, v59, v239, v239
	v_rcp_f32_e32 v58, v58
	v_rcp_f32_e32 v59, v59
	s_nop 0
	v_pk_mul_f32 v[48:49], v[48:49], v[60:61]
	s_nop 0
	v_pk_mul_f32 v[50:51], v[50:51], v[58:59]
	v_cvt_pk_bf16_f32 v58, v48, v49
	v_mad_i64_i32 v[48:49], s[0:1], v67, s9, v[112:113]
	v_cvt_pk_bf16_f32 v59, v50, v51
	v_lshl_add_u64 v[48:49], v[48:49], 0, v[114:115]
	global_store_dwordx4 v[48:49], v[56:59], off
	v_fmamk_f32 v239, v236, 0x3a800000, v194
	s_nop 0
	v_rsq_f32_e32 v48, v239
	s_nop 0
	v_mov_b32_e32 v49, v48
	v_mul_f32_e32 v48, 0xbfb8aa3b, v49
	v_pk_mul_f32 v[54:55], v[44:45], v[48:49] op_sel_hi:[1,0]
	s_nop 0
	v_pk_mul_f32 v[52:53], v[46:47], v[48:49] op_sel_hi:[1,0]
	v_exp_f32_e32 v49, v54
	s_nop 0
	v_fma_f32 v49, v49, v239, v239
	v_rcp_f32_e32 v54, v49
	v_exp_f32_e32 v49, v55
	s_nop 0
	v_fma_f32 v49, v49, v239, v239
	v_rcp_f32_e32 v55, v49
	v_exp_f32_e32 v49, v52
	s_nop 0
	v_fma_f32 v49, v49, v239, v239
	v_rcp_f32_e32 v52, v49
	v_exp_f32_e32 v49, v53
	v_pk_mul_f32 v[40:41], v[40:41], v[54:55]
	v_fma_f32 v49, v49, v239, v239
	v_rcp_f32_e32 v53, v49
	v_cvt_pk_bf16_f32 v44, v41, s0
	v_cvt_pk_bf16_f32 v40, v40, s0
	s_nop 0
	v_pk_mul_f32 v[42:43], v[42:43], v[52:53]
	s_nop 0
	v_cvt_pk_bf16_f32 v41, v42, v43
	v_lshlrev_b32_e32 v42, 16, v44
	v_pk_mul_f32 v[44:45], v[36:37], v[48:49] op_sel_hi:[1,0]
	v_or_b32_sdwa v40, v42, v40 dst_sel:DWORD dst_unused:UNUSED_PAD src0_sel:DWORD src1_sel:WORD_0
	v_pk_mul_f32 v[42:43], v[38:39], v[48:49] op_sel_hi:[1,0]
	v_exp_f32_e32 v44, v44
	v_exp_f32_e32 v45, v45
	v_exp_f32_e32 v42, v42
	v_exp_f32_e32 v43, v43
	v_fma_f32 v44, v44, v239, v239
	v_fma_f32 v45, v45, v239, v239
	v_rcp_f32_e32 v44, v44
	v_rcp_f32_e32 v45, v45
	v_fma_f32 v42, v42, v239, v239
	v_fma_f32 v43, v43, v239, v239
	v_rcp_f32_e32 v42, v42
	v_rcp_f32_e32 v43, v43
	s_nop 0
	v_pk_mul_f32 v[32:33], v[32:33], v[44:45]
	s_nop 0
	v_pk_mul_f32 v[34:35], v[34:35], v[42:43]
	v_cvt_pk_bf16_f32 v42, v32, v33
	v_mad_i64_i32 v[32:33], s[0:1], v69, s9, v[112:113]
	v_cvt_pk_bf16_f32 v43, v34, v35
	v_lshl_add_u64 v[32:33], v[32:33], 0, v[114:115]
	global_store_dwordx4 v[32:33], v[40:43], off
	v_fmamk_f32 v239, v237, 0x3a800000, v194
	s_nop 0
	v_rsq_f32_e32 v32, v239
	s_nop 0
	v_mov_b32_e32 v33, v32
	v_mul_f32_e32 v32, 0xbfb8aa3b, v33
	v_pk_mul_f32 v[38:39], v[28:29], v[32:33] op_sel_hi:[1,0]
	s_nop 0
	v_pk_mul_f32 v[36:37], v[30:31], v[32:33] op_sel_hi:[1,0]
	v_exp_f32_e32 v33, v38
	s_nop 0
	v_fma_f32 v33, v33, v239, v239
	v_rcp_f32_e32 v38, v33
	v_exp_f32_e32 v33, v39
	s_nop 0
	v_fma_f32 v33, v33, v239, v239
	v_rcp_f32_e32 v39, v33
	v_exp_f32_e32 v33, v36
	s_nop 0
	v_fma_f32 v33, v33, v239, v239
	v_rcp_f32_e32 v36, v33
	v_exp_f32_e32 v33, v37
	v_pk_mul_f32 v[24:25], v[24:25], v[38:39]
	v_fma_f32 v33, v33, v239, v239
	v_rcp_f32_e32 v37, v33
	v_cvt_pk_bf16_f32 v28, v25, s0
	v_cvt_pk_bf16_f32 v24, v24, s0
	s_nop 0
	v_pk_mul_f32 v[26:27], v[26:27], v[36:37]
	s_nop 0
	v_cvt_pk_bf16_f32 v25, v26, v27
	v_lshlrev_b32_e32 v26, 16, v28
	v_pk_mul_f32 v[28:29], v[20:21], v[32:33] op_sel_hi:[1,0]
	v_or_b32_sdwa v24, v26, v24 dst_sel:DWORD dst_unused:UNUSED_PAD src0_sel:DWORD src1_sel:WORD_0
	v_pk_mul_f32 v[26:27], v[22:23], v[32:33] op_sel_hi:[1,0]
	v_exp_f32_e32 v28, v28
	v_exp_f32_e32 v29, v29
	v_exp_f32_e32 v26, v26
	v_exp_f32_e32 v27, v27
	v_fma_f32 v28, v28, v239, v239
	v_fma_f32 v29, v29, v239, v239
	v_rcp_f32_e32 v28, v28
	v_rcp_f32_e32 v29, v29
	v_fma_f32 v26, v26, v239, v239
	v_fma_f32 v27, v27, v239, v239
	v_rcp_f32_e32 v26, v26
	v_rcp_f32_e32 v27, v27
	s_nop 0
	v_pk_mul_f32 v[16:17], v[16:17], v[28:29]
	s_nop 0
	v_pk_mul_f32 v[18:19], v[18:19], v[26:27]
	v_cvt_pk_bf16_f32 v26, v16, v17
	v_mad_i64_i32 v[16:17], s[0:1], v66, s9, v[112:113]
	v_cvt_pk_bf16_f32 v27, v18, v19
	v_lshl_add_u64 v[16:17], v[16:17], 0, v[114:115]
	global_store_dwordx4 v[16:17], v[24:27], off
	v_fmamk_f32 v239, v238, 0x3a800000, v194
	s_nop 0
	v_rsq_f32_e32 v16, v239
	s_nop 0
	v_mov_b32_e32 v17, v16
	v_mul_f32_e32 v16, 0xbfb8aa3b, v17
	v_pk_mul_f32 v[22:23], v[12:13], v[16:17] op_sel_hi:[1,0]
	s_nop 0
	v_pk_mul_f32 v[20:21], v[14:15], v[16:17] op_sel_hi:[1,0]
	v_exp_f32_e32 v17, v22
	s_and_b64 vcc, exec, s[4:5]
	v_fma_f32 v17, v17, v239, v239
	v_rcp_f32_e32 v22, v17
	v_exp_f32_e32 v17, v23
	s_nop 0
	v_fma_f32 v17, v17, v239, v239
	v_rcp_f32_e32 v23, v17
	v_exp_f32_e32 v17, v20
	s_nop 0
	v_fma_f32 v17, v17, v239, v239
	v_rcp_f32_e32 v20, v17
	v_exp_f32_e32 v17, v21
	v_pk_mul_f32 v[8:9], v[8:9], v[22:23]
	v_fma_f32 v17, v17, v239, v239
	v_rcp_f32_e32 v21, v17
	v_cvt_pk_bf16_f32 v12, v9, s0
	v_cvt_pk_bf16_f32 v8, v8, s0
	s_nop 0
	v_pk_mul_f32 v[10:11], v[10:11], v[20:21]
	s_nop 0
	v_cvt_pk_bf16_f32 v9, v10, v11
	v_lshlrev_b32_e32 v10, 16, v12
	v_pk_mul_f32 v[12:13], v[4:5], v[16:17] op_sel_hi:[1,0]
	v_or_b32_sdwa v8, v10, v8 dst_sel:DWORD dst_unused:UNUSED_PAD src0_sel:DWORD src1_sel:WORD_0
	v_pk_mul_f32 v[10:11], v[6:7], v[16:17] op_sel_hi:[1,0]
	v_exp_f32_e32 v12, v12
	v_exp_f32_e32 v13, v13
	v_exp_f32_e32 v10, v10
	v_exp_f32_e32 v11, v11
	v_fma_f32 v12, v12, v239, v239
	v_fma_f32 v13, v13, v239, v239
	v_rcp_f32_e32 v12, v12
	v_rcp_f32_e32 v13, v13
	v_fma_f32 v10, v10, v239, v239
	v_fma_f32 v11, v11, v239, v239
	v_rcp_f32_e32 v10, v10
	v_rcp_f32_e32 v11, v11
	s_nop 0
	v_pk_mul_f32 v[0:1], v[0:1], v[12:13]
	s_nop 0
	v_pk_mul_f32 v[2:3], v[2:3], v[10:11]
	v_cvt_pk_bf16_f32 v10, v0, v1
	v_mad_i64_i32 v[0:1], s[0:1], v64, s9, v[112:113]
	v_cvt_pk_bf16_f32 v11, v2, v3
	v_lshl_add_u64 v[0:1], v[0:1], 0, v[114:115]
	s_mov_b32 s0, s10
	global_store_dwordx4 v[0:1], v[8:11], off
	s_cbranch_vccz .LBB0_399
	s_waitcnt vmcnt(0)
	s_cmpk_gt_u32 s25, 0xff
	s_cbranch_scc1 .LBB0_406
	s_barrier

.LBB0_2804:
	s_add_u32 s20, s18, 0xfffc0080
	s_addc_u32 s21, s19, -1
	s_add_i32 s42, 0, 0x10000
	ds_read_b128 v[138:141], v202
	ds_read_b128 v[142:145], v202 offset:1024
	ds_read_b128 v[146:149], v202 offset:2048
	ds_read_b128 v[154:157], v202 offset:3072
	s_cmp_eq_u32 s41, 12
	s_cselect_b32 s23, s9, s21
	s_cselect_b32 s22, s33, s20
	s_cselect_b32 s21, s11, s40
	s_cselect_b32 s20, s38, s39
	s_add_i32 m0, s17, 0xc000
	ds_read_b128 v[158:161], v152
	ds_read_b128 v[162:165], v152 offset:1024
	ds_read_b128 v[166:169], v152 offset:2048
	ds_read_b128 v[170:173], v152 offset:3072
	ds_read_b128 v[174:177], v152 offset:4096
	ds_read_b128 v[178:181], v152 offset:5120
	ds_read_b128 v[182:185], v152 offset:6144
	ds_read_b128 v[186:189], v152 offset:7168
	global_load_lds_dwordx4 v136, s[18:19]
	s_add_i32 m0, s17, 0xe000
	s_nop 0
	global_load_lds_dwordx4 v134, s[18:19]
	s_waitcnt lgkmcnt(8)
	s_barrier
	s_waitcnt lgkmcnt(0)
	v_mfma_f32_16x16x32_bf16 v[124:127], v[138:141], v[158:161], v[124:127]
	v_mfma_f32_16x16x32_bf16 v[116:119], v[146:149], v[158:161], v[116:119]
	v_mfma_f32_16x16x32_bf16 v[108:111], v[138:141], v[166:169], v[108:111]
	v_mfma_f32_16x16x32_bf16 v[100:103], v[146:149], v[166:169], v[100:103]
	v_mfma_f32_16x16x32_bf16 v[92:95], v[138:141], v[174:177], v[92:95]
	v_mfma_f32_16x16x32_bf16 v[84:87], v[146:149], v[174:177], v[84:87]
	v_mfma_f32_16x16x32_bf16 v[76:79], v[138:141], v[182:185], v[76:79]
	v_mfma_f32_16x16x32_bf16 v[68:71], v[146:149], v[182:185], v[68:71]
	v_mfma_f32_16x16x32_bf16 v[124:127], v[142:145], v[162:165], v[124:127]
	v_mfma_f32_16x16x32_bf16 v[116:119], v[154:157], v[162:165], v[116:119]
	v_mfma_f32_16x16x32_bf16 v[108:111], v[142:145], v[170:173], v[108:111]
	v_mfma_f32_16x16x32_bf16 v[100:103], v[154:157], v[170:173], v[100:103]
	v_mfma_f32_16x16x32_bf16 v[92:95], v[142:145], v[178:181], v[92:95]
	v_mfma_f32_16x16x32_bf16 v[84:87], v[154:157], v[178:181], v[84:87]
	v_mfma_f32_16x16x32_bf16 v[76:79], v[142:145], v[186:189], v[76:79]
	v_mfma_f32_16x16x32_bf16 v[68:71], v[154:157], v[186:189], v[68:71]
	s_barrier
	s_add_i32 s44, 0, 0x14000
	s_add_i32 s42, s42, s28
	s_mov_b32 m0, s42
	ds_read_b128 v[198:201], v203
	ds_read_b128 v[206:209], v203 offset:1024
	ds_read_b128 v[210:213], v203 offset:2048
	ds_read_b128 v[214:217], v203 offset:3072
	global_load_lds_dwordx4 v192, s[20:21]
	s_add_i32 m0, s42, 0x2000
	s_nop 0
	global_load_lds_dwordx4 v128, s[20:21]
	s_barrier
	s_waitcnt lgkmcnt(0)
	v_mfma_f32_16x16x32_bf16 v[120:123], v[198:201], v[158:161], v[120:123]
	v_mfma_f32_16x16x32_bf16 v[112:115], v[210:213], v[158:161], v[112:115]
	v_mfma_f32_16x16x32_bf16 v[104:107], v[198:201], v[166:169], v[104:107]
	v_mfma_f32_16x16x32_bf16 v[96:99], v[210:213], v[166:169], v[96:99]
	v_mfma_f32_16x16x32_bf16 v[88:91], v[198:201], v[174:177], v[88:91]
	v_mfma_f32_16x16x32_bf16 v[80:83], v[210:213], v[174:177], v[80:83]
	v_mfma_f32_16x16x32_bf16 v[72:75], v[198:201], v[182:185], v[72:75]
	v_mfma_f32_16x16x32_bf16 v[64:67], v[210:213], v[182:185], v[64:67]
	v_mfma_f32_16x16x32_bf16 v[120:123], v[206:209], v[162:165], v[120:123]
	v_mfma_f32_16x16x32_bf16 v[112:115], v[214:217], v[162:165], v[112:115]
	v_mfma_f32_16x16x32_bf16 v[104:107], v[206:209], v[170:173], v[104:107]
	v_mfma_f32_16x16x32_bf16 v[96:99], v[214:217], v[170:173], v[96:99]
	v_mfma_f32_16x16x32_bf16 v[88:91], v[206:209], v[178:181], v[88:91]
	v_mfma_f32_16x16x32_bf16 v[80:83], v[214:217], v[178:181], v[80:83]
	v_mfma_f32_16x16x32_bf16 v[72:75], v[206:209], v[186:189], v[72:75]
	v_mfma_f32_16x16x32_bf16 v[64:67], v[214:217], v[186:189], v[64:67]
	s_mov_b32 m0, s17
	s_add_u32 vcc_lo, s22, 0x80
	s_addc_u32 vcc_hi, s23, 0
	s_barrier
	ds_read_b128 v[158:161], v152 offset:16384
	ds_read_b128 v[162:165], v152 offset:17408
	ds_read_b128 v[166:169], v152 offset:18432
	ds_read_b128 v[170:173], v152 offset:19456
	ds_read_b128 v[174:177], v152 offset:20480
	ds_read_b128 v[178:181], v152 offset:21504
	ds_read_b128 v[182:185], v152 offset:22528
	ds_read_b128 v[186:189], v152 offset:23552
	global_load_lds_dwordx4 v132, s[22:23]
	s_mov_b32 m0, s29
	s_nop 0
	global_load_lds_dwordx4 v130, s[22:23]
	s_barrier
	s_waitcnt lgkmcnt(0)
	v_mfma_f32_16x16x32_bf16 v[60:63], v[138:141], v[158:161], v[60:63]
	v_mfma_f32_16x16x32_bf16 v[52:55], v[146:149], v[158:161], v[52:55]
	v_mfma_f32_16x16x32_bf16 v[44:47], v[138:141], v[166:169], v[44:47]
	v_mfma_f32_16x16x32_bf16 v[36:39], v[146:149], v[166:169], v[36:39]
	v_mfma_f32_16x16x32_bf16 v[28:31], v[138:141], v[174:177], v[28:31]
	v_mfma_f32_16x16x32_bf16 v[20:23], v[146:149], v[174:177], v[20:23]
	v_mfma_f32_16x16x32_bf16 v[12:15], v[138:141], v[182:185], v[12:15]
	v_mfma_f32_16x16x32_bf16 v[4:7], v[146:149], v[182:185], v[4:7]
	v_mfma_f32_16x16x32_bf16 v[60:63], v[142:145], v[162:165], v[60:63]
	v_mfma_f32_16x16x32_bf16 v[52:55], v[154:157], v[162:165], v[52:55]
	v_mfma_f32_16x16x32_bf16 v[44:47], v[142:145], v[170:173], v[44:47]
	v_mfma_f32_16x16x32_bf16 v[36:39], v[154:157], v[170:173], v[36:39]
	v_mfma_f32_16x16x32_bf16 v[28:31], v[142:145], v[178:181], v[28:31]
	v_mfma_f32_16x16x32_bf16 v[20:23], v[154:157], v[178:181], v[20:23]
	v_mfma_f32_16x16x32_bf16 v[12:15], v[142:145], v[186:189], v[12:15]
	v_mfma_f32_16x16x32_bf16 v[4:7], v[154:157], v[186:189], v[4:7]
	s_barrier
	s_add_u32 s42, s20, 0x40000
	s_addc_u32 s43, s21, 0
	s_add_i32 s44, s44, s28
	s_mov_b32 m0, s44
	s_nop 0
	global_load_lds_dwordx4 v192, s[42:43]
	s_add_i32 m0, s44, 0x2000
	s_nop 0
	global_load_lds_dwordx4 v128, s[42:43]
	s_waitcnt vmcnt(6)
	s_barrier
	v_mfma_f32_16x16x32_bf16 v[56:59], v[198:201], v[158:161], v[56:59]
	v_mfma_f32_16x16x32_bf16 v[48:51], v[210:213], v[158:161], v[48:51]
	v_mfma_f32_16x16x32_bf16 v[40:43], v[198:201], v[166:169], v[40:43]
	v_mfma_f32_16x16x32_bf16 v[32:35], v[210:213], v[166:169], v[32:35]
	v_mfma_f32_16x16x32_bf16 v[24:27], v[198:201], v[174:177], v[24:27]
	v_mfma_f32_16x16x32_bf16 v[16:19], v[210:213], v[174:177], v[16:19]
	v_mfma_f32_16x16x32_bf16 v[8:11], v[198:201], v[182:185], v[8:11]
	v_mfma_f32_16x16x32_bf16 v[0:3], v[210:213], v[182:185], v[0:3]
	v_mfma_f32_16x16x32_bf16 v[56:59], v[206:209], v[162:165], v[56:59]
	v_mfma_f32_16x16x32_bf16 v[48:51], v[214:217], v[162:165], v[48:51]
	v_mfma_f32_16x16x32_bf16 v[40:43], v[206:209], v[170:173], v[40:43]
	v_mfma_f32_16x16x32_bf16 v[32:35], v[214:217], v[170:173], v[32:35]
	v_mfma_f32_16x16x32_bf16 v[24:27], v[206:209], v[178:181], v[24:27]
	v_mfma_f32_16x16x32_bf16 v[16:19], v[214:217], v[178:181], v[16:19]
	v_mfma_f32_16x16x32_bf16 v[8:11], v[206:209], v[186:189], v[8:11]
	v_mfma_f32_16x16x32_bf16 v[0:3], v[214:217], v[186:189], v[0:3]
	s_add_i32 s42, 0, 0x18000
	s_barrier
	ds_read_b128 v[138:141], v204
	ds_read_b128 v[142:145], v204 offset:1024
	ds_read_b128 v[146:149], v204 offset:2048
	ds_read_b128 v[154:157], v204 offset:3072
	s_add_u32 s22, s22, 0x40000
	s_addc_u32 s23, s23, 0
	s_mov_b32 m0, s30
	ds_read_b128 v[158:161], v152 offset:32768
	ds_read_b128 v[162:165], v152 offset:33792
	ds_read_b128 v[166:169], v152 offset:34816
	ds_read_b128 v[170:173], v152 offset:35840
	ds_read_b128 v[174:177], v152 offset:36864
	ds_read_b128 v[178:181], v152 offset:37888
	ds_read_b128 v[182:185], v152 offset:38912
	ds_read_b128 v[186:189], v152 offset:39936
	global_load_lds_dwordx4 v132, s[22:23]
	s_mov_b32 m0, s31
	s_nop 0
	global_load_lds_dwordx4 v130, s[22:23]
	s_waitcnt lgkmcnt(8)
	s_barrier
	s_waitcnt lgkmcnt(0)
	v_mfma_f32_16x16x32_bf16 v[124:127], v[138:141], v[158:161], v[124:127]
	v_mfma_f32_16x16x32_bf16 v[116:119], v[146:149], v[158:161], v[116:119]
	v_mfma_f32_16x16x32_bf16 v[108:111], v[138:141], v[166:169], v[108:111]
	v_mfma_f32_16x16x32_bf16 v[100:103], v[146:149], v[166:169], v[100:103]
	v_mfma_f32_16x16x32_bf16 v[92:95], v[138:141], v[174:177], v[92:95]
	v_mfma_f32_16x16x32_bf16 v[84:87], v[146:149], v[174:177], v[84:87]
	v_mfma_f32_16x16x32_bf16 v[76:79], v[138:141], v[182:185], v[76:79]
	v_mfma_f32_16x16x32_bf16 v[68:71], v[146:149], v[182:185], v[68:71]
	v_mfma_f32_16x16x32_bf16 v[124:127], v[142:145], v[162:165], v[124:127]
	v_mfma_f32_16x16x32_bf16 v[116:119], v[154:157], v[162:165], v[116:119]
	v_mfma_f32_16x16x32_bf16 v[108:111], v[142:145], v[170:173], v[108:111]
	v_mfma_f32_16x16x32_bf16 v[100:103], v[154:157], v[170:173], v[100:103]
	v_mfma_f32_16x16x32_bf16 v[92:95], v[142:145], v[178:181], v[92:95]
	v_mfma_f32_16x16x32_bf16 v[84:87], v[154:157], v[178:181], v[84:87]
	v_mfma_f32_16x16x32_bf16 v[76:79], v[142:145], v[186:189], v[76:79]
	v_mfma_f32_16x16x32_bf16 v[68:71], v[154:157], v[186:189], v[68:71]
	s_barrier
	s_add_i32 s22, 0, 0x1c000
	s_add_i32 s23, s42, s28
	s_add_u32 s100, s20, 0x80
	s_addc_u32 s101, s21, 0
	s_mov_b32 m0, s23
	ds_read_b128 v[198:201], v205
	ds_read_b128 v[206:209], v205 offset:1024
	ds_read_b128 v[210:213], v205 offset:2048
	ds_read_b128 v[214:217], v205 offset:3072
	global_load_lds_dwordx4 v192, s[100:101]
	s_add_i32 m0, s23, 0x2000
	s_nop 0
	global_load_lds_dwordx4 v128, s[100:101]
	s_barrier
	s_waitcnt lgkmcnt(0)
	v_mfma_f32_16x16x32_bf16 v[120:123], v[198:201], v[158:161], v[120:123]
	v_mfma_f32_16x16x32_bf16 v[112:115], v[210:213], v[158:161], v[112:115]
	v_mfma_f32_16x16x32_bf16 v[104:107], v[198:201], v[166:169], v[104:107]
	v_mfma_f32_16x16x32_bf16 v[96:99], v[210:213], v[166:169], v[96:99]
	v_mfma_f32_16x16x32_bf16 v[88:91], v[198:201], v[174:177], v[88:91]
	v_mfma_f32_16x16x32_bf16 v[80:83], v[210:213], v[174:177], v[80:83]
	v_mfma_f32_16x16x32_bf16 v[72:75], v[198:201], v[182:185], v[72:75]
	v_mfma_f32_16x16x32_bf16 v[64:67], v[210:213], v[182:185], v[64:67]
	v_mfma_f32_16x16x32_bf16 v[120:123], v[206:209], v[162:165], v[120:123]
	v_mfma_f32_16x16x32_bf16 v[112:115], v[214:217], v[162:165], v[112:115]
	v_mfma_f32_16x16x32_bf16 v[104:107], v[206:209], v[170:173], v[104:107]
	v_mfma_f32_16x16x32_bf16 v[96:99], v[214:217], v[170:173], v[96:99]
	v_mfma_f32_16x16x32_bf16 v[88:91], v[206:209], v[178:181], v[88:91]
	v_mfma_f32_16x16x32_bf16 v[80:83], v[214:217], v[178:181], v[80:83]
	v_mfma_f32_16x16x32_bf16 v[72:75], v[206:209], v[186:189], v[72:75]
	v_mfma_f32_16x16x32_bf16 v[64:67], v[214:217], v[186:189], v[64:67]
	s_mov_b32 m0, s34
	s_barrier
	ds_read_b128 v[158:161], v152 offset:49152
	ds_read_b128 v[162:165], v152 offset:50176
	ds_read_b128 v[166:169], v152 offset:51200
	ds_read_b128 v[170:173], v152 offset:52224
	ds_read_b128 v[174:177], v152 offset:53248
	ds_read_b128 v[178:181], v152 offset:54272
	ds_read_b128 v[182:185], v152 offset:55296
	ds_read_b128 v[186:189], v152 offset:56320
	global_load_lds_dwordx4 v132, vcc
	s_mov_b32 m0, s35
	s_nop 0
	global_load_lds_dwordx4 v130, vcc
	s_barrier
	s_waitcnt lgkmcnt(0)
	v_mfma_f32_16x16x32_bf16 v[60:63], v[138:141], v[158:161], v[60:63]
	v_mfma_f32_16x16x32_bf16 v[52:55], v[146:149], v[158:161], v[52:55]
	v_mfma_f32_16x16x32_bf16 v[44:47], v[138:141], v[166:169], v[44:47]
	v_mfma_f32_16x16x32_bf16 v[36:39], v[146:149], v[166:169], v[36:39]
	v_mfma_f32_16x16x32_bf16 v[28:31], v[138:141], v[174:177], v[28:31]
	v_mfma_f32_16x16x32_bf16 v[20:23], v[146:149], v[174:177], v[20:23]
	v_mfma_f32_16x16x32_bf16 v[12:15], v[138:141], v[182:185], v[12:15]
	v_mfma_f32_16x16x32_bf16 v[4:7], v[146:149], v[182:185], v[4:7]
	v_mfma_f32_16x16x32_bf16 v[60:63], v[142:145], v[162:165], v[60:63]
	v_mfma_f32_16x16x32_bf16 v[52:55], v[154:157], v[162:165], v[52:55]
	v_mfma_f32_16x16x32_bf16 v[44:47], v[142:145], v[170:173], v[44:47]
	v_mfma_f32_16x16x32_bf16 v[36:39], v[154:157], v[170:173], v[36:39]
	v_mfma_f32_16x16x32_bf16 v[28:31], v[142:145], v[178:181], v[28:31]
	v_mfma_f32_16x16x32_bf16 v[20:23], v[154:157], v[178:181], v[20:23]
	v_mfma_f32_16x16x32_bf16 v[12:15], v[142:145], v[186:189], v[12:15]
	v_mfma_f32_16x16x32_bf16 v[4:7], v[154:157], v[186:189], v[4:7]
	s_barrier
	s_add_u32 s20, s20, 0x40080
	s_addc_u32 s21, s21, 0
	s_add_i32 s22, s22, s28
	s_mov_b32 m0, s22
	s_nop 0
	global_load_lds_dwordx4 v192, s[20:21]
	s_add_i32 m0, s22, 0x2000
	s_nop 0
	global_load_lds_dwordx4 v128, s[20:21]
	s_waitcnt vmcnt(6)
	s_barrier
	v_mfma_f32_16x16x32_bf16 v[56:59], v[198:201], v[158:161], v[56:59]
	v_mfma_f32_16x16x32_bf16 v[48:51], v[210:213], v[158:161], v[48:51]
	v_mfma_f32_16x16x32_bf16 v[40:43], v[198:201], v[166:169], v[40:43]
	v_mfma_f32_16x16x32_bf16 v[32:35], v[210:213], v[166:169], v[32:35]
	v_mfma_f32_16x16x32_bf16 v[24:27], v[198:201], v[174:177], v[24:27]
	v_mfma_f32_16x16x32_bf16 v[16:19], v[210:213], v[174:177], v[16:19]
	v_mfma_f32_16x16x32_bf16 v[8:11], v[198:201], v[182:185], v[8:11]
	v_mfma_f32_16x16x32_bf16 v[0:3], v[210:213], v[182:185], v[0:3]
	v_mfma_f32_16x16x32_bf16 v[56:59], v[206:209], v[162:165], v[56:59]
	v_mfma_f32_16x16x32_bf16 v[48:51], v[214:217], v[162:165], v[48:51]
	v_mfma_f32_16x16x32_bf16 v[40:43], v[206:209], v[170:173], v[40:43]
	v_mfma_f32_16x16x32_bf16 v[32:35], v[214:217], v[170:173], v[32:35]
	v_mfma_f32_16x16x32_bf16 v[24:27], v[206:209], v[178:181], v[24:27]
	v_mfma_f32_16x16x32_bf16 v[16:19], v[214:217], v[178:181], v[16:19]
	v_mfma_f32_16x16x32_bf16 v[8:11], v[206:209], v[186:189], v[8:11]
	v_mfma_f32_16x16x32_bf16 v[0:3], v[214:217], v[186:189], v[0:3]
	s_add_i32 s41, s41, 2
	s_add_u32 s39, s39, 0x100
	s_addc_u32 s40, s40, 0
	s_add_u32 s18, s18, 0x100
	s_addc_u32 s19, s19, 0
	s_cmp_gt_u32 s41, 13
	s_barrier
	s_cbranch_scc0 .LBB0_2804
	v_mov_b32_e32 v139, v252
	s_lshl_b32 s11, s16, 8
	v_readfirstlane_b32 s9, v139
	s_ashr_i32 s16, s9, 2
	s_andn2_b32 s16, s16, 63
	s_lshr_b32 s9, s9, 1
	s_add_i32 s16, s16, s11
	s_lshl_b32 s11, s37, 7
	s_and_b32 s9, s9, 0x60
	v_and_or_b32 v138, v139, 15, s16
	s_or_b32 s9, s9, s11
	v_lshrrev_b32_e32 v139, 1, v139
	v_and_or_b32 v148, v139, 24, s9
	v_ashrrev_i32_e32 v139, 31, v138
	v_lshl_add_u64 v[140:141], v[138:139], 2, s[6:7]
	v_or_b32_e32 v146, 16, v138
	v_ashrrev_i32_e32 v147, 31, v146
	v_lshl_add_u64 v[142:143], v[146:147], 2, s[6:7]
	v_or_b32_e32 v144, 32, v138
	v_ashrrev_i32_e32 v145, 31, v144
	v_lshl_add_u64 v[142:143], v[144:145], 2, s[6:7]
	v_or_b32_e32 v142, 48, v138
	v_ashrrev_i32_e32 v143, 31, v142
	v_lshl_add_u64 v[154:155], v[142:143], 2, s[6:7]
	v_pk_mul_f32 v[120:121], v[124:125], v[120:121]
	v_pk_mul_f32 v[122:123], v[126:127], v[122:123]
	v_pk_mul_f32 v[112:113], v[116:117], v[112:113]
	v_pk_mul_f32 v[114:115], v[118:119], v[114:115]
	v_ashrrev_i32_e32 v149, 31, v148
	s_movk_i32 s9, 0x1600
	v_pk_mul_f32 v[104:105], v[108:109], v[104:105]
	v_pk_mul_f32 v[106:107], v[110:111], v[106:107]
	v_pk_mul_f32 v[96:97], v[100:101], v[96:97]
	v_pk_mul_f32 v[98:99], v[102:103], v[98:99]
	v_pk_mul_f32 v[88:89], v[92:93], v[88:89]
	v_pk_mul_f32 v[90:91], v[94:95], v[90:91]
	v_pk_mul_f32 v[80:81], v[84:85], v[80:81]
	v_pk_mul_f32 v[82:83], v[86:87], v[82:83]
	v_pk_mul_f32 v[72:73], v[76:77], v[72:73]
	v_pk_mul_f32 v[74:75], v[78:79], v[74:75]
	v_pk_mul_f32 v[64:65], v[68:69], v[64:65]
	v_pk_mul_f32 v[66:67], v[70:71], v[66:67]
	v_pk_mul_f32 v[56:57], v[60:61], v[56:57]
	v_pk_mul_f32 v[58:59], v[62:63], v[58:59]
	v_pk_mul_f32 v[48:49], v[52:53], v[48:49]
	v_pk_mul_f32 v[50:51], v[54:55], v[50:51]
	v_pk_mul_f32 v[40:41], v[44:45], v[40:41]
	v_pk_mul_f32 v[42:43], v[46:47], v[42:43]
	v_pk_mul_f32 v[32:33], v[36:37], v[32:33]
	v_pk_mul_f32 v[34:35], v[38:39], v[34:35]
	v_pk_mul_f32 v[24:25], v[28:29], v[24:25]
	v_pk_mul_f32 v[26:27], v[30:31], v[26:27]
	v_pk_mul_f32 v[16:17], v[20:21], v[16:17]
	v_pk_mul_f32 v[18:19], v[22:23], v[18:19]
	v_pk_mul_f32 v[8:9], v[12:13], v[8:9]
	v_pk_mul_f32 v[10:11], v[14:15], v[10:11]
	v_pk_mul_f32 v[0:1], v[4:5], v[0:1]
	v_pk_mul_f32 v[2:3], v[6:7], v[2:3]
	s_mov_b32 s37, s10
	s_mov_b32 s16, s8
	s_mov_b64 s[20:21], s[12:13]
	v_fmamk_f32 v239, v231, 0x3a800000, v194
	s_nop 0
	v_rsq_f32_e32 v143, v239
	s_nop 0
	v_mul_f32_e32 v154, 0xbfb8aa3b, v143
	v_pk_mul_f32 v[158:159], v[124:125], v[154:155] op_sel_hi:[1,0]
	s_nop 0
	v_exp_f32_e32 v143, v158
	v_pk_mul_f32 v[156:157], v[126:127], v[154:155] op_sel_hi:[1,0]
	v_fma_f32 v143, v143, v239, v239
	v_rcp_f32_e32 v158, v143
	v_exp_f32_e32 v143, v159
	s_nop 0
	v_fma_f32 v143, v143, v239, v239
	v_rcp_f32_e32 v159, v143
	v_exp_f32_e32 v143, v156
	s_nop 0
	v_fma_f32 v143, v143, v239, v239
	v_rcp_f32_e32 v156, v143
	v_exp_f32_e32 v143, v157
	v_pk_mul_f32 v[120:121], v[120:121], v[158:159]
	v_fma_f32 v143, v143, v239, v239
	v_rcp_f32_e32 v157, v143
	v_cvt_pk_bf16_f32 v124, v121, s0
	v_cvt_pk_bf16_f32 v120, v120, s0
	s_nop 0
	v_pk_mul_f32 v[122:123], v[122:123], v[156:157]
	s_nop 0
	v_cvt_pk_bf16_f32 v121, v122, v123
	v_lshlrev_b32_e32 v122, 16, v124
	v_pk_mul_f32 v[124:125], v[116:117], v[154:155] op_sel_hi:[1,0]
	v_or_b32_sdwa v120, v122, v120 dst_sel:DWORD dst_unused:UNUSED_PAD src0_sel:DWORD src1_sel:WORD_0
	v_pk_mul_f32 v[122:123], v[118:119], v[154:155] op_sel_hi:[1,0]
	v_exp_f32_e32 v124, v124
	v_exp_f32_e32 v125, v125
	v_exp_f32_e32 v122, v122
	v_exp_f32_e32 v123, v123
	v_fma_f32 v124, v124, v239, v239
	v_fma_f32 v125, v125, v239, v239
	v_rcp_f32_e32 v124, v124
	v_rcp_f32_e32 v125, v125
	v_fma_f32 v122, v122, v239, v239
	v_fma_f32 v123, v123, v239, v239
	v_rcp_f32_e32 v122, v122
	v_rcp_f32_e32 v123, v123
	s_nop 0
	v_pk_mul_f32 v[112:113], v[112:113], v[124:125]
	s_nop 0
	v_pk_mul_f32 v[114:115], v[114:115], v[122:123]
	v_cvt_pk_bf16_f32 v122, v112, v113
	v_mov_b64_e32 v[112:113], s[4:5]
	v_cvt_pk_bf16_f32 v123, v114, v115
	v_mad_i64_i32 v[116:117], s[18:19], v138, s9, v[112:113]
	v_lshlrev_b64 v[114:115], 1, v[148:149]
	v_lshl_add_u64 v[116:117], v[116:117], 0, v[114:115]
	global_store_dwordx4 v[116:117], v[120:123], off
	v_fmamk_f32 v239, v232, 0x3a800000, v194
	s_nop 0
	v_rsq_f32_e32 v116, v239
	s_nop 0
	v_mul_f32_e32 v118, 0xbfb8aa3b, v116
	v_pk_mul_f32 v[122:123], v[108:109], v[118:119] op_sel_hi:[1,0]
	v_pk_mul_f32 v[120:121], v[110:111], v[118:119] op_sel_hi:[1,0]
	v_exp_f32_e32 v117, v122
	s_nop 0
	v_fma_f32 v117, v117, v239, v239
	v_rcp_f32_e32 v122, v117
	v_exp_f32_e32 v117, v123
	s_nop 0
	v_fma_f32 v117, v117, v239, v239
	v_rcp_f32_e32 v123, v117
	v_exp_f32_e32 v117, v120
	s_nop 0
	v_fma_f32 v117, v117, v239, v239
	v_rcp_f32_e32 v120, v117
	v_exp_f32_e32 v117, v121
	s_nop 0
	v_fma_f32 v117, v117, v239, v239
	v_rcp_f32_e32 v121, v117
	s_nop 0
	v_pk_mul_f32 v[104:105], v[104:105], v[122:123]
	s_nop 0
	v_pk_mul_f32 v[106:107], v[106:107], v[120:121]
	v_cvt_pk_bf16_f32 v108, v105, s0
	v_cvt_pk_bf16_f32 v104, v104, s0
	v_cvt_pk_bf16_f32 v105, v106, v107
	v_lshlrev_b32_e32 v106, 16, v108
	v_pk_mul_f32 v[108:109], v[100:101], v[118:119] op_sel_hi:[1,0]
	v_or_b32_sdwa v104, v106, v104 dst_sel:DWORD dst_unused:UNUSED_PAD src0_sel:DWORD src1_sel:WORD_0
	v_pk_mul_f32 v[106:107], v[102:103], v[118:119] op_sel_hi:[1,0]
	v_exp_f32_e32 v108, v108
	v_exp_f32_e32 v109, v109
	v_exp_f32_e32 v106, v106
	v_exp_f32_e32 v107, v107
	v_fma_f32 v108, v108, v239, v239
	v_fma_f32 v109, v109, v239, v239
	v_rcp_f32_e32 v108, v108
	v_rcp_f32_e32 v109, v109
	v_fma_f32 v106, v106, v239, v239
	v_fma_f32 v107, v107, v239, v239
	v_rcp_f32_e32 v106, v106
	v_rcp_f32_e32 v107, v107
	s_nop 0
	v_pk_mul_f32 v[96:97], v[96:97], v[108:109]
	s_nop 0
	v_pk_mul_f32 v[98:99], v[98:99], v[106:107]
	v_cvt_pk_bf16_f32 v106, v96, v97
	v_mad_i64_i32 v[96:97], s[18:19], v146, s9, v[112:113]
	v_cvt_pk_bf16_f32 v107, v98, v99
	v_lshl_add_u64 v[96:97], v[96:97], 0, v[114:115]
	global_store_dwordx4 v[96:97], v[104:107], off
	v_fmamk_f32 v239, v233, 0x3a800000, v194
	s_nop 0
	v_rsq_f32_e32 v96, v239
	s_nop 0
	v_mov_b32_e32 v97, v96
	v_mul_f32_e32 v96, 0xbfb8aa3b, v97
	v_pk_mul_f32 v[102:103], v[92:93], v[96:97] op_sel_hi:[1,0]
	s_nop 0
	v_pk_mul_f32 v[100:101], v[94:95], v[96:97] op_sel_hi:[1,0]
	v_exp_f32_e32 v97, v102
	s_nop 0
	v_fma_f32 v97, v97, v239, v239
	v_rcp_f32_e32 v102, v97
	v_exp_f32_e32 v97, v103
	s_nop 0
	v_fma_f32 v97, v97, v239, v239
	v_rcp_f32_e32 v103, v97
	v_exp_f32_e32 v97, v100
	s_nop 0
	v_fma_f32 v97, v97, v239, v239
	v_rcp_f32_e32 v100, v97
	v_exp_f32_e32 v97, v101
	v_pk_mul_f32 v[88:89], v[88:89], v[102:103]
	v_fma_f32 v97, v97, v239, v239
	v_rcp_f32_e32 v101, v97
	v_cvt_pk_bf16_f32 v92, v89, s0
	v_cvt_pk_bf16_f32 v88, v88, s0
	s_nop 0
	v_pk_mul_f32 v[90:91], v[90:91], v[100:101]
	s_nop 0
	v_cvt_pk_bf16_f32 v89, v90, v91
	v_lshlrev_b32_e32 v90, 16, v92
	v_pk_mul_f32 v[92:93], v[84:85], v[96:97] op_sel_hi:[1,0]
	v_or_b32_sdwa v88, v90, v88 dst_sel:DWORD dst_unused:UNUSED_PAD src0_sel:DWORD src1_sel:WORD_0
	v_pk_mul_f32 v[90:91], v[86:87], v[96:97] op_sel_hi:[1,0]
	v_exp_f32_e32 v92, v92
	v_exp_f32_e32 v93, v93
	v_exp_f32_e32 v90, v90
	v_exp_f32_e32 v91, v91
	v_fma_f32 v92, v92, v239, v239
	v_fma_f32 v93, v93, v239, v239
	v_rcp_f32_e32 v92, v92
	v_rcp_f32_e32 v93, v93
	v_fma_f32 v90, v90, v239, v239
	v_fma_f32 v91, v91, v239, v239
	v_rcp_f32_e32 v90, v90
	v_rcp_f32_e32 v91, v91
	s_nop 0
	v_pk_mul_f32 v[80:81], v[80:81], v[92:93]
	s_nop 0
	v_pk_mul_f32 v[82:83], v[82:83], v[90:91]
	v_cvt_pk_bf16_f32 v90, v80, v81
	v_mad_i64_i32 v[80:81], s[18:19], v144, s9, v[112:113]
	v_cvt_pk_bf16_f32 v91, v82, v83
	v_lshl_add_u64 v[80:81], v[80:81], 0, v[114:115]
	global_store_dwordx4 v[80:81], v[88:91], off
	v_fmamk_f32 v239, v234, 0x3a800000, v194
	s_nop 0
	v_rsq_f32_e32 v80, v239
	s_nop 0
	v_mov_b32_e32 v81, v80
	v_mul_f32_e32 v80, 0xbfb8aa3b, v81
	v_pk_mul_f32 v[86:87], v[76:77], v[80:81] op_sel_hi:[1,0]
	s_nop 0
	v_pk_mul_f32 v[84:85], v[78:79], v[80:81] op_sel_hi:[1,0]
	v_exp_f32_e32 v81, v86
	s_nop 0
	v_fma_f32 v81, v81, v239, v239
	v_rcp_f32_e32 v86, v81
	v_exp_f32_e32 v81, v87
	s_nop 0
	v_fma_f32 v81, v81, v239, v239
	v_rcp_f32_e32 v87, v81
	v_exp_f32_e32 v81, v84
	s_nop 0
	v_fma_f32 v81, v81, v239, v239
	v_rcp_f32_e32 v84, v81
	v_exp_f32_e32 v81, v85
	v_pk_mul_f32 v[72:73], v[72:73], v[86:87]
	v_fma_f32 v81, v81, v239, v239
	v_rcp_f32_e32 v85, v81
	v_cvt_pk_bf16_f32 v76, v73, s0
	v_cvt_pk_bf16_f32 v72, v72, s0
	s_nop 0
	v_pk_mul_f32 v[74:75], v[74:75], v[84:85]
	s_nop 0
	v_cvt_pk_bf16_f32 v73, v74, v75
	v_lshlrev_b32_e32 v74, 16, v76
	v_pk_mul_f32 v[76:77], v[68:69], v[80:81] op_sel_hi:[1,0]
	v_or_b32_sdwa v72, v74, v72 dst_sel:DWORD dst_unused:UNUSED_PAD src0_sel:DWORD src1_sel:WORD_0
	v_pk_mul_f32 v[74:75], v[70:71], v[80:81] op_sel_hi:[1,0]
	v_exp_f32_e32 v76, v76
	v_exp_f32_e32 v77, v77
	v_exp_f32_e32 v74, v74
	v_exp_f32_e32 v75, v75
	v_fma_f32 v76, v76, v239, v239
	v_fma_f32 v77, v77, v239, v239
	v_rcp_f32_e32 v76, v76
	v_rcp_f32_e32 v77, v77
	v_fma_f32 v74, v74, v239, v239
	v_fma_f32 v75, v75, v239, v239
	v_rcp_f32_e32 v74, v74
	v_rcp_f32_e32 v75, v75
	s_nop 0
	v_pk_mul_f32 v[64:65], v[64:65], v[76:77]
	v_add_u32_e32 v69, 0x90, v138
	s_nop 0
	v_pk_mul_f32 v[66:67], v[66:67], v[74:75]
	v_cvt_pk_bf16_f32 v74, v64, v65
	v_mad_i64_i32 v[64:65], s[18:19], v142, s9, v[112:113]
	v_cvt_pk_bf16_f32 v75, v66, v67
	v_lshl_add_u64 v[64:65], v[64:65], 0, v[114:115]
	global_store_dwordx4 v[64:65], v[72:75], off
	v_add_u32_e32 v67, 0x80, v138
	v_add_u32_e32 v66, 0xa0, v138
	v_add_u32_e32 v64, 0xb0, v138
	v_fmamk_f32 v239, v235, 0x3a800000, v194
	s_nop 0
	v_rsq_f32_e32 v68, v239
	s_nop 0
	v_mov_b32_e32 v70, v68
	v_mul_f32_e32 v68, 0xbfb8aa3b, v70
	v_pk_mul_f32 v[74:75], v[60:61], v[68:69] op_sel_hi:[1,0]
	v_pk_mul_f32 v[72:73], v[62:63], v[68:69] op_sel_hi:[1,0]
	v_exp_f32_e32 v74, v74
	v_exp_f32_e32 v75, v75
	v_exp_f32_e32 v72, v72
	v_exp_f32_e32 v73, v73
	v_fma_f32 v74, v74, v239, v239
	v_fma_f32 v75, v75, v239, v239
	v_rcp_f32_e32 v74, v74
	v_rcp_f32_e32 v75, v75
	v_fma_f32 v72, v72, v239, v239
	v_fma_f32 v73, v73, v239, v239
	v_rcp_f32_e32 v72, v72
	v_rcp_f32_e32 v73, v73
	s_nop 0
	s_nop 0
	v_pk_mul_f32 v[56:57], v[56:57], v[74:75]
	s_nop 0
	v_pk_mul_f32 v[58:59], v[58:59], v[72:73]
	v_cvt_pk_bf16_f32 v60, v57, s0
	v_cvt_pk_bf16_f32 v56, v56, s0
	v_cvt_pk_bf16_f32 v57, v58, v59
	v_lshlrev_b32_e32 v58, 16, v60
	v_pk_mul_f32 v[60:61], v[52:53], v[68:69] op_sel_hi:[1,0]
	v_or_b32_sdwa v56, v58, v56 dst_sel:DWORD dst_unused:UNUSED_PAD src0_sel:DWORD src1_sel:WORD_0
	v_pk_mul_f32 v[58:59], v[54:55], v[68:69] op_sel_hi:[1,0]
	v_exp_f32_e32 v60, v60
	v_exp_f32_e32 v61, v61
	v_exp_f32_e32 v58, v58
	v_exp_f32_e32 v59, v59
	v_fma_f32 v60, v60, v239, v239
	v_fma_f32 v61, v61, v239, v239
	v_rcp_f32_e32 v60, v60
	v_rcp_f32_e32 v61, v61
	v_fma_f32 v58, v58, v239, v239
	v_fma_f32 v59, v59, v239, v239
	v_rcp_f32_e32 v58, v58
	v_rcp_f32_e32 v59, v59
	s_nop 0
	v_pk_mul_f32 v[48:49], v[48:49], v[60:61]
	s_nop 0
	v_pk_mul_f32 v[50:51], v[50:51], v[58:59]
	v_cvt_pk_bf16_f32 v58, v48, v49
	v_mad_i64_i32 v[48:49], s[18:19], v67, s9, v[112:113]
	v_cvt_pk_bf16_f32 v59, v50, v51
	v_lshl_add_u64 v[48:49], v[48:49], 0, v[114:115]
	global_store_dwordx4 v[48:49], v[56:59], off
	v_fmamk_f32 v239, v236, 0x3a800000, v194
	s_nop 0
	v_rsq_f32_e32 v48, v239
	s_nop 0
	v_mov_b32_e32 v49, v48
	v_mul_f32_e32 v48, 0xbfb8aa3b, v49
	v_pk_mul_f32 v[54:55], v[44:45], v[48:49] op_sel_hi:[1,0]
	s_nop 0
	v_pk_mul_f32 v[52:53], v[46:47], v[48:49] op_sel_hi:[1,0]
	v_exp_f32_e32 v49, v54
	s_nop 0
	v_fma_f32 v49, v49, v239, v239
	v_rcp_f32_e32 v54, v49
	v_exp_f32_e32 v49, v55
	s_nop 0
	v_fma_f32 v49, v49, v239, v239
	v_rcp_f32_e32 v55, v49
	v_exp_f32_e32 v49, v52
	s_nop 0
	v_fma_f32 v49, v49, v239, v239
	v_rcp_f32_e32 v52, v49
	v_exp_f32_e32 v49, v53
	v_pk_mul_f32 v[40:41], v[40:41], v[54:55]
	v_fma_f32 v49, v49, v239, v239
	v_rcp_f32_e32 v53, v49
	v_cvt_pk_bf16_f32 v44, v41, s0
	v_cvt_pk_bf16_f32 v40, v40, s0
	s_nop 0
	v_pk_mul_f32 v[42:43], v[42:43], v[52:53]
	s_nop 0
	v_cvt_pk_bf16_f32 v41, v42, v43
	v_lshlrev_b32_e32 v42, 16, v44
	v_pk_mul_f32 v[44:45], v[36:37], v[48:49] op_sel_hi:[1,0]
	v_or_b32_sdwa v40, v42, v40 dst_sel:DWORD dst_unused:UNUSED_PAD src0_sel:DWORD src1_sel:WORD_0
	v_pk_mul_f32 v[42:43], v[38:39], v[48:49] op_sel_hi:[1,0]
	v_exp_f32_e32 v44, v44
	v_exp_f32_e32 v45, v45
	v_exp_f32_e32 v42, v42
	v_exp_f32_e32 v43, v43
	v_fma_f32 v44, v44, v239, v239
	v_fma_f32 v45, v45, v239, v239
	v_rcp_f32_e32 v44, v44
	v_rcp_f32_e32 v45, v45
	v_fma_f32 v42, v42, v239, v239
	v_fma_f32 v43, v43, v239, v239
	v_rcp_f32_e32 v42, v42
	v_rcp_f32_e32 v43, v43
	s_nop 0
	v_pk_mul_f32 v[32:33], v[32:33], v[44:45]
	s_nop 0
	v_pk_mul_f32 v[34:35], v[34:35], v[42:43]
	v_cvt_pk_bf16_f32 v42, v32, v33
	v_mad_i64_i32 v[32:33], s[18:19], v69, s9, v[112:113]
	v_cvt_pk_bf16_f32 v43, v34, v35
	v_lshl_add_u64 v[32:33], v[32:33], 0, v[114:115]
	global_store_dwordx4 v[32:33], v[40:43], off
	v_fmamk_f32 v239, v237, 0x3a800000, v194
	s_nop 0
	v_rsq_f32_e32 v32, v239
	s_nop 0
	v_mov_b32_e32 v33, v32
	v_mul_f32_e32 v32, 0xbfb8aa3b, v33
	v_pk_mul_f32 v[38:39], v[28:29], v[32:33] op_sel_hi:[1,0]
	s_nop 0
	v_pk_mul_f32 v[36:37], v[30:31], v[32:33] op_sel_hi:[1,0]
	v_exp_f32_e32 v33, v38
	s_nop 0
	v_fma_f32 v33, v33, v239, v239
	v_rcp_f32_e32 v38, v33
	v_exp_f32_e32 v33, v39
	s_nop 0
	v_fma_f32 v33, v33, v239, v239
	v_rcp_f32_e32 v39, v33
	v_exp_f32_e32 v33, v36
	s_nop 0
	v_fma_f32 v33, v33, v239, v239
	v_rcp_f32_e32 v36, v33
	v_exp_f32_e32 v33, v37
	v_pk_mul_f32 v[24:25], v[24:25], v[38:39]
	v_fma_f32 v33, v33, v239, v239
	v_rcp_f32_e32 v37, v33
	v_cvt_pk_bf16_f32 v28, v25, s0
	v_cvt_pk_bf16_f32 v24, v24, s0
	s_nop 0
	v_pk_mul_f32 v[26:27], v[26:27], v[36:37]
	s_nop 0
	v_cvt_pk_bf16_f32 v25, v26, v27
	v_lshlrev_b32_e32 v26, 16, v28
	v_pk_mul_f32 v[28:29], v[20:21], v[32:33] op_sel_hi:[1,0]
	v_or_b32_sdwa v24, v26, v24 dst_sel:DWORD dst_unused:UNUSED_PAD src0_sel:DWORD src1_sel:WORD_0
	v_pk_mul_f32 v[26:27], v[22:23], v[32:33] op_sel_hi:[1,0]
	v_exp_f32_e32 v28, v28
	v_exp_f32_e32 v29, v29
	v_exp_f32_e32 v26, v26
	v_exp_f32_e32 v27, v27
	v_fma_f32 v28, v28, v239, v239
	v_fma_f32 v29, v29, v239, v239
	v_rcp_f32_e32 v28, v28
	v_rcp_f32_e32 v29, v29
	v_fma_f32 v26, v26, v239, v239
	v_fma_f32 v27, v27, v239, v239
	v_rcp_f32_e32 v26, v26
	v_rcp_f32_e32 v27, v27
	s_nop 0
	v_pk_mul_f32 v[16:17], v[16:17], v[28:29]
	s_nop 0
	v_pk_mul_f32 v[18:19], v[18:19], v[26:27]
	v_cvt_pk_bf16_f32 v26, v16, v17
	v_mad_i64_i32 v[16:17], s[18:19], v66, s9, v[112:113]
	v_cvt_pk_bf16_f32 v27, v18, v19
	v_lshl_add_u64 v[16:17], v[16:17], 0, v[114:115]
	global_store_dwordx4 v[16:17], v[24:27], off
	v_fmamk_f32 v239, v238, 0x3a800000, v194
	s_nop 0
	v_rsq_f32_e32 v16, v239
	s_nop 0
	v_mov_b32_e32 v17, v16
	v_mul_f32_e32 v16, 0xbfb8aa3b, v17
	v_pk_mul_f32 v[22:23], v[12:13], v[16:17] op_sel_hi:[1,0]
	s_nop 0
	v_pk_mul_f32 v[20:21], v[14:15], v[16:17] op_sel_hi:[1,0]
	v_exp_f32_e32 v17, v22
	s_and_b64 vcc, exec, s[0:1]
	v_fma_f32 v17, v17, v239, v239
	v_rcp_f32_e32 v22, v17
	v_exp_f32_e32 v17, v23
	s_nop 0
	v_fma_f32 v17, v17, v239, v239
	v_rcp_f32_e32 v23, v17
	v_exp_f32_e32 v17, v20
	s_nop 0
	v_fma_f32 v17, v17, v239, v239
	v_rcp_f32_e32 v20, v17
	v_exp_f32_e32 v17, v21
	v_pk_mul_f32 v[8:9], v[8:9], v[22:23]
	v_fma_f32 v17, v17, v239, v239
	v_rcp_f32_e32 v21, v17
	v_cvt_pk_bf16_f32 v12, v9, s0
	v_cvt_pk_bf16_f32 v8, v8, s0
	s_nop 0
	v_pk_mul_f32 v[10:11], v[10:11], v[20:21]
	s_nop 0
	v_cvt_pk_bf16_f32 v9, v10, v11
	v_lshlrev_b32_e32 v10, 16, v12
	v_pk_mul_f32 v[12:13], v[4:5], v[16:17] op_sel_hi:[1,0]
	v_or_b32_sdwa v8, v10, v8 dst_sel:DWORD dst_unused:UNUSED_PAD src0_sel:DWORD src1_sel:WORD_0
	v_pk_mul_f32 v[10:11], v[6:7], v[16:17] op_sel_hi:[1,0]
	v_exp_f32_e32 v12, v12
	v_exp_f32_e32 v13, v13
	v_exp_f32_e32 v10, v10
	v_exp_f32_e32 v11, v11
	v_fma_f32 v12, v12, v239, v239
	v_fma_f32 v13, v13, v239, v239
	v_rcp_f32_e32 v12, v12
	v_rcp_f32_e32 v13, v13
	v_fma_f32 v10, v10, v239, v239
	v_fma_f32 v11, v11, v239, v239
	v_rcp_f32_e32 v10, v10
	v_rcp_f32_e32 v11, v11
	s_nop 0
	v_pk_mul_f32 v[0:1], v[0:1], v[12:13]
	s_nop 0
	v_pk_mul_f32 v[2:3], v[2:3], v[10:11]
	v_cvt_pk_bf16_f32 v10, v0, v1
	v_mad_i64_i32 v[0:1], s[18:19], v64, s9, v[112:113]
	v_cvt_pk_bf16_f32 v11, v2, v3
	v_lshl_add_u64 v[0:1], v[0:1], 0, v[114:115]
	s_mov_b64 s[18:19], s[14:15]
	global_store_dwordx4 v[0:1], v[8:11], off
	s_cbranch_vccz .LBB0_2801
	s_waitcnt vmcnt(0)
	s_cmpk_gt_u32 s25, 0xff
	s_cbranch_scc1 .LBB0_2808
	s_barrier
